# attention unit prologue: K/V tiles 0 and 1 by LDS-DMA issued right after the Q-row loads (two load round trips per unit overlap the Q post-processing)
# speedup vs baseline: 1.0012x; 1.0006x over previous
.LBB0_535:
	v_mov_b32_e32 v166, v0
	v_mov_b64_e32 v[2:3], s[0:1]
	v_readfirstlane_b32 s40, v166
	s_ashr_i32 s21, s40, 6
	v_and_b32_e32 v167, 31, v166
	s_lshl_b32 s22, s21, 5
	v_bfe_u32 v168, v166, 5, 1
	v_or_b32_e32 v170, s22, v167
	v_mad_i64_i32 v[2:3], s[0:1], v170, s19, v[2:3]
	v_lshlrev_b32_e32 v164, 4, v168
	v_mov_b32_e32 v165, v131
	s_waitcnt vmcnt(0)
	v_lshl_add_u64 v[30:31], v[2:3], 0, v[164:165]
	global_load_dwordx4 v[2:5], v[30:31], off
	global_load_dwordx4 v[6:9], v[30:31], off offset:32
	global_load_dwordx4 v[10:13], v[30:31], off offset:64
	global_load_dwordx4 v[14:17], v[30:31], off offset:96
	global_load_dwordx4 v[18:21], v[30:31], off offset:128
	global_load_dwordx4 v[22:25], v[30:31], off offset:160
	global_load_dwordx4 v[26:29], v[30:31], off offset:192
	s_nop 0
	global_load_dwordx4 v[30:33], v[30:31], off offset:224
	v_mbcnt_lo_u32_b32 v172, -1, 0
	v_mbcnt_hi_u32_b32 v172, -1, v172
	v_lshrrev_b32_e32 v173, 4, v172
	v_and_b32_e32 v250, 15, v172
	v_xor_b32_e32 v250, v250, v173
	s_and_b32 s101, s21, 1
	s_lshl_b32 s101, s101, 3
	v_xor_b32_e32 v250, s101, v250
	v_lshlrev_b32_e32 v251, 4, v250
	s_lshl_b32 s100, s21, 3
	v_add_u32_e32 v250, s100, v173
	s_and_b32 s100, s21, 1
	s_lshl_b32 s100, s100, 2
	s_lshr_b32 s101, s21, 1
	s_lshl_b32 s101, s101, 4
	s_or_b32 s100, s100, s101
	v_bfe_u32 v173, v172, 2, 2
	v_or_b32_e32 v173, s100, v173
	v_bfe_u32 v174, v172, 4, 1
	v_lshl_or_b32 v173, v174, 3, v173
	v_lshl_or_b32 v250, v173, 8, v250
	v_lshrrev_b32_e32 v173, 5, v172
	v_and_b32_e32 v174, 3, v172
	v_lshlrev_b32_e32 v174, 4, v174
	v_lshl_or_b32 v173, v173, 6, v174
	v_lshl_or_b32 v251, v173, 8, v251
	s_lshl_b32 s100, s28, 1
	v_and_b32_e32 v222, 0xff, v250
	v_and_b32_e32 v223, 0xff, v251
	v_lshrrev_b32_e32 v224, 8, v250
	v_lshrrev_b32_e32 v225, 8, v251
	v_mad_u32_u24 v224, v224, s100, v225
	v_add_u32_e32 v225, 0x80, v224
	v_mad_u32_u24 v226, v222, s100, v223
	v_xor_b32_e32 v223, 64, v223
	v_add_u32_e32 v222, 4, v222
	v_mad_u32_u24 v227, v222, s100, v223
	s_lshl_b32 s101, s21, 11
	s_add_i32 m0, s101, 0x8000
	s_lshl_b32 s100, s28, 7
	global_load_lds_dwordx4 v226, s[96:97]
	s_add_i32 m0, s101, 0x8400
	s_add_u32 s98, s96, s100
	global_load_lds_dwordx4 v227, s[96:97]
	s_mov_b32 m0, s101
	s_addc_u32 s99, s97, 0
	global_load_lds_dwordx4 v224, s[50:51]
	s_add_i32 m0, s101, 0x400
	s_nop 0
	global_load_lds_dwordx4 v225, s[50:51]
	s_add_i32 m0, s101, 0xc000
	s_nop 0
	global_load_lds_dwordx4 v226, s[98:99]
	s_add_i32 m0, s101, 0xc400
	s_nop 0
	global_load_lds_dwordx4 v227, s[98:99]
	s_add_u32 s98, s50, s100
	s_addc_u32 s99, s51, 0
	s_add_i32 m0, s101, 0x4000
	s_nop 0
	global_load_lds_dwordx4 v224, s[98:99]
	s_add_i32 m0, s101, 0x4400
	s_nop 0
	global_load_lds_dwordx4 v225, s[98:99]
	s_cmp_lg_u32 s39, 0
	s_cbranch_scc0 .LBB0_595
	s_bitcmp1_b32 s39, 0
	s_cselect_b64 s[30:31], -1, 0
	s_mov_b64 s[0:1], -1
	s_and_b64 vcc, exec, s[30:31]
	s_waitcnt vmcnt(14)
	v_lshlrev_b32_e32 v80, 16, v6
	v_and_b32_e32 v81, 0xffff0000, v6
	v_lshlrev_b32_e32 v78, 16, v7
	v_and_b32_e32 v79, 0xffff0000, v7
	v_lshlrev_b32_e32 v76, 16, v8
	v_and_b32_e32 v77, 0xffff0000, v8
	v_lshlrev_b32_e32 v74, 16, v9
	v_and_b32_e32 v75, 0xffff0000, v9
	v_and_b32_e32 v97, 0xffff0000, v2
	v_lshlrev_b32_e32 v96, 16, v2
	s_waitcnt vmcnt(13)
	v_and_b32_e32 v91, 0xffff0000, v10
	v_lshlrev_b32_e32 v90, 16, v10
	v_and_b32_e32 v99, 0xffff0000, v3
	v_lshlrev_b32_e32 v98, 16, v3
	v_and_b32_e32 v93, 0xffff0000, v11
	v_lshlrev_b32_e32 v92, 16, v11
	v_and_b32_e32 v103, 0xffff0000, v4
	v_lshlrev_b32_e32 v102, 16, v4
	v_and_b32_e32 v95, 0xffff0000, v12
	v_lshlrev_b32_e32 v94, 16, v12
	v_and_b32_e32 v101, 0xffff0000, v5
	v_lshlrev_b32_e32 v100, 16, v5
	v_and_b32_e32 v89, 0xffff0000, v13
	v_lshlrev_b32_e32 v88, 16, v13
	s_waitcnt vmcnt(12)
	v_lshlrev_b32_e32 v86, 16, v14
	v_and_b32_e32 v87, 0xffff0000, v14
	v_lshlrev_b32_e32 v84, 16, v15
	v_and_b32_e32 v85, 0xffff0000, v15
	v_lshlrev_b32_e32 v82, 16, v16
	v_and_b32_e32 v83, 0xffff0000, v16
	v_lshlrev_b32_e32 v72, 16, v17
	v_and_b32_e32 v73, 0xffff0000, v17
	s_waitcnt vmcnt(11)
	v_lshlrev_b32_e32 v58, 16, v18
	v_and_b32_e32 v59, 0xffff0000, v18
	v_lshlrev_b32_e32 v56, 16, v19
	v_and_b32_e32 v57, 0xffff0000, v19
	v_lshlrev_b32_e32 v54, 16, v20
	v_and_b32_e32 v55, 0xffff0000, v20
	v_lshlrev_b32_e32 v52, 16, v21
	v_and_b32_e32 v53, 0xffff0000, v21
	s_waitcnt vmcnt(10)
	v_lshlrev_b32_e32 v48, 16, v22
	v_and_b32_e32 v49, 0xffff0000, v22
	v_lshlrev_b32_e32 v46, 16, v23
	v_and_b32_e32 v47, 0xffff0000, v23
	v_lshlrev_b32_e32 v42, 16, v24
	v_and_b32_e32 v43, 0xffff0000, v24
	v_lshlrev_b32_e32 v36, 16, v25
	v_and_b32_e32 v37, 0xffff0000, v25
	s_waitcnt vmcnt(9)
	v_lshlrev_b32_e32 v64, 16, v26
	v_and_b32_e32 v65, 0xffff0000, v26
	v_lshlrev_b32_e32 v62, 16, v27
	v_and_b32_e32 v63, 0xffff0000, v27
	v_lshlrev_b32_e32 v60, 16, v28
	v_and_b32_e32 v61, 0xffff0000, v28
	v_lshlrev_b32_e32 v50, 16, v29
	v_and_b32_e32 v51, 0xffff0000, v29
	s_waitcnt vmcnt(8)
	v_and_b32_e32 v45, 0xffff0000, v30
	v_lshlrev_b32_e32 v44, 16, v30
	v_and_b32_e32 v41, 0xffff0000, v31
	v_lshlrev_b32_e32 v40, 16, v31
	v_and_b32_e32 v39, 0xffff0000, v32
	v_lshlrev_b32_e32 v38, 16, v32
	v_and_b32_e32 v35, 0xffff0000, v33
	v_lshlrev_b32_e32 v34, 16, v33
	s_cbranch_vccz .LBB0_538
	v_pk_mul_f32 v[66:67], v[96:97], v[96:97]
	v_pk_mul_f32 v[70:71], v[98:99], v[98:99]
	v_add_f32_e32 v66, v66, v67
	v_add_f32_e32 v66, v70, v66
	v_pk_mul_f32 v[106:107], v[102:103], v[102:103]
	v_add_f32_e32 v66, v71, v66
	v_add_f32_e32 v66, v106, v66
	v_pk_mul_f32 v[110:111], v[100:101], v[100:101]
	v_add_f32_e32 v66, v107, v66
	v_add_f32_e32 v66, v110, v66
	v_add_f32_e32 v66, v111, v66
	v_fmac_f32_e32 v66, v80, v80
	v_fmac_f32_e32 v66, v81, v81
	v_fmac_f32_e32 v66, v78, v78
	v_fmac_f32_e32 v66, v79, v79
	v_fmac_f32_e32 v66, v76, v76
	v_fmac_f32_e32 v66, v77, v77
	v_fmac_f32_e32 v66, v74, v74
	v_pk_mul_f32 v[68:69], v[90:91], v[90:91]
	v_fmac_f32_e32 v66, v75, v75
	v_add_f32_e32 v66, v68, v66
	v_pk_mul_f32 v[104:105], v[92:93], v[92:93]
	v_add_f32_e32 v66, v69, v66
	v_add_f32_e32 v66, v104, v66
	v_pk_mul_f32 v[108:109], v[94:95], v[94:95]
	v_add_f32_e32 v66, v105, v66
	v_add_f32_e32 v66, v108, v66
	v_add_f32_e32 v68, v109, v66
	v_pk_mul_f32 v[66:67], v[88:89], v[88:89]
	s_nop 0
	v_add_f32_e32 v66, v66, v68
	v_add_f32_e32 v68, v67, v66
	v_fmac_f32_e32 v68, v86, v86
	v_fmac_f32_e32 v68, v87, v87
	v_fmac_f32_e32 v68, v84, v84
	v_fmac_f32_e32 v68, v85, v85
	v_fmac_f32_e32 v68, v82, v82
	v_fmac_f32_e32 v68, v83, v83
	v_fmac_f32_e32 v68, v72, v72
	v_fmac_f32_e32 v68, v73, v73
	v_fmac_f32_e32 v68, v58, v58
	v_fmac_f32_e32 v68, v59, v59
	v_fmac_f32_e32 v68, v56, v56
	v_fmac_f32_e32 v68, v57, v57
	v_fmac_f32_e32 v68, v54, v54
	v_fmac_f32_e32 v68, v55, v55
	v_fmac_f32_e32 v68, v52, v52
	v_fmac_f32_e32 v68, v53, v53
	v_fmac_f32_e32 v68, v48, v48
	v_fmac_f32_e32 v68, v49, v49
	v_fmac_f32_e32 v68, v46, v46
	v_fmac_f32_e32 v68, v47, v47
	v_fmac_f32_e32 v68, v42, v42
	v_fmac_f32_e32 v68, v43, v43
	v_fmac_f32_e32 v68, v36, v36
	v_fmac_f32_e32 v68, v37, v37
	v_fmac_f32_e32 v68, v64, v64
	v_fmac_f32_e32 v68, v65, v65
	v_fmac_f32_e32 v68, v62, v62
	v_fmac_f32_e32 v68, v63, v63
	v_fmac_f32_e32 v68, v60, v60
	v_fmac_f32_e32 v68, v61, v61
	v_fmac_f32_e32 v68, v50, v50
	v_fmac_f32_e32 v68, v51, v51
	v_pk_mul_f32 v[66:67], v[44:45], v[44:45]
	s_nop 0
	v_add_f32_e32 v66, v66, v68
	v_add_f32_e32 v68, v67, v66
	v_pk_mul_f32 v[66:67], v[40:41], v[40:41]
	s_nop 0
	v_add_f32_e32 v66, v66, v68
	v_add_f32_e32 v68, v67, v66
	v_pk_mul_f32 v[66:67], v[38:39], v[38:39]
	s_nop 0
	v_add_f32_e32 v66, v66, v68
	v_add_f32_e32 v68, v67, v66
	v_pk_mul_f32 v[66:67], v[34:35], v[34:35]
	s_nop 0
	v_add_f32_e32 v66, v66, v68
	v_and_b32_e32 v68, 64, v202
	v_add_f32_e32 v66, v67, v66
	v_xor_b32_e32 v67, 32, v202
	v_add_u32_e32 v68, 64, v68
	v_cmp_lt_i32_e32 vcc, v67, v68
	s_nop 1
	v_cndmask_b32_e32 v67, v202, v67, vcc
	v_lshlrev_b32_e32 v67, 2, v67
	ds_bpermute_b32 v67, v67, v66
	s_waitcnt lgkmcnt(0)
	v_add_f32_e32 v66, v66, v67
	v_fmamk_f32 v66, v66, 0x3c000000, v1
	v_mul_f32_e32 v67, 0x4f800000, v66
	v_cmp_gt_f32_e32 vcc, s75, v66
	s_nop 1
	v_cndmask_b32_e32 v66, v66, v67, vcc
	v_sqrt_f32_e32 v67, v66
	s_nop 0
	v_add_u32_e32 v68, -1, v67
	v_fma_f32 v69, -v68, v67, v66
	v_cmp_ge_f32_e64 s[0:1], 0, v69
	v_add_u32_e32 v69, 1, v67
	s_nop 0
	v_cndmask_b32_e64 v68, v67, v68, s[0:1]
	v_fma_f32 v67, -v69, v67, v66
	v_cmp_lt_f32_e64 s[0:1], 0, v67
	s_nop 1
	v_cndmask_b32_e64 v67, v68, v69, s[0:1]
	v_mul_f32_e32 v68, 0x37800000, v67
	v_cndmask_b32_e32 v67, v67, v68, vcc
	v_cmp_class_f32_e32 vcc, v66, v200
	s_nop 1
	v_cndmask_b32_e32 v66, v67, v66, vcc
	v_div_scale_f32 v67, s[0:1], v66, v66, 1.0
	v_rcp_f32_e32 v68, v67
	s_mov_b64 s[0:1], 0
	v_fma_f32 v69, -v67, v68, 1.0
	v_fmac_f32_e32 v68, v69, v68
	v_div_scale_f32 v69, vcc, 1.0, v66, 1.0
	v_mul_f32_e32 v70, v69, v68
	v_fma_f32 v71, -v67, v70, v69
	v_fmac_f32_e32 v70, v71, v68
	v_fma_f32 v67, -v67, v70, v69
	v_div_fmas_f32 v67, v67, v68, v70
	v_div_fixup_f32 v66, v67, v66, 1.0

.LBB0_557:
	s_waitcnt vmcnt(15)
	v_mov_b64_e32 v[138:139], v[4:5]
	s_waitcnt vmcnt(14)
	v_mov_b64_e32 v[146:147], v[8:9]
	s_waitcnt vmcnt(13)
	v_mov_b64_e32 v[134:135], v[12:13]
	s_waitcnt vmcnt(12)
	v_mov_b64_e32 v[142:143], v[16:17]
	s_waitcnt vmcnt(11)
	v_mov_b64_e32 v[154:155], v[20:21]
	s_waitcnt vmcnt(10)
	v_mov_b64_e32 v[162:163], v[24:25]
	s_waitcnt vmcnt(9)
	v_mov_b64_e32 v[150:151], v[28:29]
	s_waitcnt vmcnt(8)
	v_mov_b64_e32 v[158:159], v[32:33]
	v_mov_b64_e32 v[136:137], v[2:3]
	v_mov_b64_e32 v[144:145], v[6:7]
	v_mov_b64_e32 v[132:133], v[10:11]
	v_mov_b64_e32 v[140:141], v[14:15]
	v_mov_b64_e32 v[152:153], v[18:19]
	v_mov_b64_e32 v[160:161], v[22:23]
	v_mov_b64_e32 v[148:149], v[26:27]
	v_mov_b64_e32 v[156:157], v[30:31]
.LBB0_558:
	v_ashrrev_i32_e32 v179, 4, v166
	s_waitcnt vmcnt(7)
	v_and_b32_e32 v4, 0xfffff0, v179
	v_lshlrev_b32_e32 v5, 1, v179
	v_lshlrev_b32_e32 v2, 3, v166
	v_and_or_b32 v4, v5, 8, v4
	v_and_b32_e32 v3, 0x78, v2
	v_lshrrev_b32_e32 v5, 1, v179
	v_lshrrev_b32_e32 v4, 1, v4
	v_bfe_u32 v2, v2, 5, 2
	s_waitcnt vmcnt(6)
	v_and_b32_e32 v6, 3, v179
	v_or_b32_e32 v4, v4, v2
	v_and_or_b32 v5, v5, 4, v6
	v_lshlrev_b32_e32 v130, 1, v3
	v_lshlrev_b32_e32 v4, 9, v4
	v_lshlrev_b32_e32 v5, 6, v5
	v_and_b32_e32 v3, 48, v130
	v_add_u32_e32 v181, 32, v179
	s_waitcnt vmcnt(3)
	v_or3_b32 v18, v4, v5, v3
	v_and_b32_e32 v4, 0xfffff0, v181
	v_lshlrev_b32_e32 v6, 1, v181
	v_and_or_b32 v4, v6, 8, v4
	v_lshrrev_b32_e32 v4, 1, v4
	v_or_b32_e32 v2, v4, v2
	v_and_b32_e32 v165, 63, v166
	v_lshlrev_b32_e32 v2, 9, v2
	v_or3_b32 v19, v2, v5, v3
	v_lshlrev_b32_e32 v3, 4, v165
	s_and_b32 s0, s40, 0x3fffffc0
	v_lshlrev_b32_e32 v2, 3, v165
	v_and_b32_e32 v3, 0xc0, v3
	v_lshlrev_b32_e32 v4, 1, v165
	s_lshl_b32 s0, s0, 2
	v_and_or_b32 v3, v2, 24, v3
	v_and_b32_e32 v4, 32, v4
	v_and_b32_e32 v2, 0x100, v2
	s_add_i32 s70, s0, 0
	v_or3_b32 v171, v3, v4, v2
	v_mad_i64_i32 v[2:3], s[0:1], s28, v179, 0
	v_lshlrev_b64 v[34:35], 1, v[2:3]
	v_lshl_add_u64 v[2:3], s[50:51], 0, v[34:35]
	v_lshl_add_u64 v[2:3], v[2:3], 0, v[130:131]
	v_mad_i64_i32 v[6:7], s[0:1], s28, v181, 0
	v_lshlrev_b64 v[36:37], 1, v[6:7]
	v_lshl_add_u64 v[6:7], s[50:51], 0, v[36:37]
	v_lshl_add_u64 v[10:11], s[96:97], 0, v[34:35]
	v_lshl_add_u64 v[14:15], s[96:97], 0, v[36:37]
	v_lshl_add_u64 v[6:7], v[6:7], 0, v[130:131]
	v_lshl_add_u64 v[10:11], v[10:11], 0, v[130:131]
	v_lshl_add_u64 v[14:15], v[14:15], 0, v[130:131]
	v_add_u32_e32 v187, 0, v18
	v_add_u32_e32 v188, 0, v19
	s_waitcnt vmcnt(0)
	s_movk_i32 s0, 0xf0
	v_lshl_add_u32 v47, v167, 8, 0
	s_add_i32 s70, s70, 0x10000
	v_add_u32_e32 v176, 0, v171
	v_lshl_add_u32 v177, v167, 2, s70
	v_lshlrev_b32_e32 v2, 8, v179
	v_and_b32_e32 v3, 0xf0, v166
	v_bitop3_b32 v2, v130, v2, v3 bitop3:0xde
	v_add_u32_e32 v191, 0, v2
	v_lshlrev_b32_e32 v2, 8, v181
	v_bitop3_b32 v2, v130, v2, v3 bitop3:0xde
	v_add_u32_e32 v192, 0, v2
	v_lshlrev_b32_e32 v2, 4, v167
	v_and_b32_e32 v46, 0xf0, v2
	v_bitop3_b32 v2, v164, v2, s0 bitop3:0x78
	v_add_u32_e32 v180, v47, v2
	s_waitcnt lgkmcnt(0)
	s_barrier
	ds_read_b128 v[2:5], v180 offset:32768
	ds_read_b128 v[6:9], v180 offset:40960
	s_waitcnt lgkmcnt(1)
	v_mfma_f32_32x32x16_bf16 v[18:33], v[2:5], v[136:139], 0
	v_bitop3_b32 v38, v164, v46, 32 bitop3:0x36
	v_add_u32_e32 v182, v47, v38
	ds_read_b128 v[38:41], v182 offset:32768
	ds_read_b128 v[42:45], v182 offset:40960
	s_movk_i32 s0, 0x60
	s_waitcnt lgkmcnt(2)
	v_mfma_f32_32x32x16_bf16 v[2:17], v[6:9], v[136:139], 0
	s_waitcnt lgkmcnt(1)
	v_mfma_f32_32x32x16_bf16 v[18:33], v[38:41], v[144:147], v[18:33]
	v_bitop3_b32 v38, v164, v46, 64 bitop3:0x36
	v_add_u32_e32 v183, v47, v38
	s_waitcnt lgkmcnt(0)
	v_mfma_f32_32x32x16_bf16 v[2:17], v[42:45], v[144:147], v[2:17]
	ds_read_b128 v[38:41], v183 offset:32768
	ds_read_b128 v[42:45], v183 offset:40960
	s_waitcnt lgkmcnt(1)
	v_mfma_f32_32x32x16_bf16 v[18:33], v[38:41], v[132:135], v[18:33]
	v_bitop3_b32 v38, v164, v46, s0 bitop3:0x36
	v_add_u32_e32 v184, v47, v38
	s_movk_i32 s0, 0x80
	s_waitcnt lgkmcnt(0)
	v_mfma_f32_32x32x16_bf16 v[2:17], v[42:45], v[132:135], v[2:17]
	ds_read_b128 v[38:41], v184 offset:32768
	ds_read_b128 v[42:45], v184 offset:40960
	s_waitcnt lgkmcnt(1)
	v_mfma_f32_32x32x16_bf16 v[18:33], v[38:41], v[140:143], v[18:33]
	v_bitop3_b32 v38, v164, v46, s0 bitop3:0x36
	v_add_u32_e32 v185, v47, v38
	s_movk_i32 s0, 0xa0
	s_waitcnt lgkmcnt(0)
	v_mfma_f32_32x32x16_bf16 v[2:17], v[42:45], v[140:143], v[2:17]
	ds_read_b128 v[38:41], v185 offset:32768
	ds_read_b128 v[42:45], v185 offset:40960
	s_waitcnt lgkmcnt(1)
	v_mfma_f32_32x32x16_bf16 v[18:33], v[38:41], v[152:155], v[18:33]
	v_bitop3_b32 v38, v164, v46, s0 bitop3:0x36
	v_add_u32_e32 v186, v47, v38
	s_movk_i32 s0, 0xc0
	s_waitcnt lgkmcnt(0)
	v_mfma_f32_32x32x16_bf16 v[2:17], v[42:45], v[152:155], v[2:17]
	ds_read_b128 v[38:41], v186 offset:32768
	ds_read_b128 v[42:45], v186 offset:40960
	s_waitcnt lgkmcnt(1)
	v_mfma_f32_32x32x16_bf16 v[18:33], v[38:41], v[160:163], v[18:33]
	v_bitop3_b32 v38, v164, v46, s0 bitop3:0x36
	v_add_u32_e32 v189, v47, v38
	s_movk_i32 s0, 0xe0
	s_waitcnt lgkmcnt(0)
	v_mfma_f32_32x32x16_bf16 v[2:17], v[42:45], v[160:163], v[2:17]
	ds_read_b128 v[38:41], v189 offset:32768
	ds_read_b128 v[42:45], v189 offset:40960
	s_waitcnt lgkmcnt(1)
	v_mfma_f32_32x32x16_bf16 v[18:33], v[38:41], v[148:151], v[18:33]
	v_bitop3_b32 v38, v164, v46, s0 bitop3:0x36
	v_add_u32_e32 v190, v47, v38
	s_waitcnt lgkmcnt(0)
	v_mfma_f32_32x32x16_bf16 v[2:17], v[42:45], v[148:151], v[2:17]
	ds_read_b128 v[38:41], v190 offset:32768
	ds_read_b128 v[42:45], v190 offset:40960
	s_waitcnt lgkmcnt(1)
	v_mfma_f32_32x32x16_bf16 v[18:33], v[38:41], v[156:159], v[18:33]
	s_waitcnt lgkmcnt(0)
	v_mfma_f32_32x32x16_bf16 v[2:17], v[42:45], v[156:159], v[2:17]
	s_nop 9
	v_max_f32_e32 v38, v19, v19
	v_max_f32_e32 v39, v18, v18
	v_max_f32_e32 v38, v39, v38
	v_max3_f32 v38, v38, v20, v21
	v_max3_f32 v38, v38, v22, v23
	v_max3_f32 v38, v38, v24, v25
	v_max3_f32 v38, v38, v26, v27
	v_max3_f32 v38, v38, v28, v29
	v_max3_f32 v38, v38, v30, v31
	v_max3_f32 v38, v38, v32, v33
	v_max3_f32 v38, v38, v2, v3
	v_max3_f32 v38, v38, v4, v5
	v_max3_f32 v38, v38, v6, v7
	v_max3_f32 v38, v38, v8, v9
	v_max3_f32 v38, v38, v10, v11
	v_max3_f32 v38, v38, v12, v13
	v_max3_f32 v38, v38, v14, v15
	v_max3_f32 v38, v38, v16, v17
	v_mov_b32_e32 v39, v38
	s_nop 1
	v_permlane32_swap_b32_e32 v38, v39
	v_max_f32_e32 v39, v39, v39
	v_max_f32_e32 v38, v38, v38
	v_max_f32_e32 v38, v38, v39
	v_add_f32_e32 v39, 0x7149f2ca, v38
	v_max_f32_e32 v38, 0xf149f2ca, v38
	v_cmp_ge_f32_e32 vcc, s91, v39
	v_sub_f32_e32 v39, 0xf149f2ca, v38
	v_mul_f32_e32 v39, 0x3e0293ee, v39
	s_cmp_eq_u64 vcc, exec
	v_exp_f32_e32 v39, v39
	s_cselect_b64 vcc, -1, 0
	s_lshl_b32 s30, s28, 7
	v_cndmask_b32_e32 v193, v38, v206, vcc
	s_add_u32 s0, s96, s30
	v_mul_f32_e32 v38, 0xbe0293ee, v193
	s_addc_u32 s1, s97, 0
	v_cndmask_b32_e64 v194, v39, 1.0, vcc
	v_mov_b32_e32 v39, v38
	s_add_u32 s30, s50, s30
	v_fmac_f32_e32 v39, 0x3e0293ee, v33
	s_addc_u32 s31, s51, 0
	v_pk_fma_f32 v[98:99], v[2:3], s[90:91], v[38:39] op_sel_hi:[1,0,0]
	v_lshl_add_u64 v[2:3], s[30:31], 0, v[34:35]
	v_pk_fma_f32 v[102:103], v[6:7], s[90:91], v[38:39] op_sel_hi:[1,0,0]
	v_lshl_add_u64 v[2:3], v[2:3], 0, v[130:131]
	v_lshl_add_u64 v[6:7], s[30:31], 0, v[36:37]
	v_pk_fma_f32 v[106:107], v[10:11], s[90:91], v[38:39] op_sel_hi:[1,0,0]
	v_pk_fma_f32 v[100:101], v[4:5], s[90:91], v[38:39] op_sel_hi:[1,0,0]
	v_lshl_add_u64 v[6:7], v[6:7], 0, v[130:131]
	v_lshl_add_u64 v[10:11], s[0:1], 0, v[34:35]
	v_pk_fma_f32 v[110:111], v[14:15], s[90:91], v[38:39] op_sel_hi:[1,0,0]
	v_pk_fma_f32 v[104:105], v[8:9], s[90:91], v[38:39] op_sel_hi:[1,0,0]
	v_lshl_add_u64 v[10:11], v[10:11], 0, v[130:131]
	v_lshl_add_u64 v[14:15], s[0:1], 0, v[36:37]
	v_pk_fma_f32 v[108:109], v[12:13], s[90:91], v[38:39] op_sel_hi:[1,0,0]
	v_lshl_add_u64 v[14:15], v[14:15], 0, v[130:131]
	v_pk_fma_f32 v[112:113], v[16:17], s[90:91], v[38:39] op_sel_hi:[1,0,0]
	v_fmamk_f32 v18, v18, 0x3e0293ee, v38
	v_fmamk_f32 v19, v19, 0x3e0293ee, v38
	v_fmamk_f32 v20, v20, 0x3e0293ee, v38
	v_fmamk_f32 v21, v21, 0x3e0293ee, v38
	v_fmamk_f32 v22, v22, 0x3e0293ee, v38
	v_fmamk_f32 v23, v23, 0x3e0293ee, v38
	v_fmamk_f32 v24, v24, 0x3e0293ee, v38
	v_fmamk_f32 v25, v25, 0x3e0293ee, v38
	v_fmamk_f32 v26, v26, 0x3e0293ee, v38
	v_fmamk_f32 v27, v27, 0x3e0293ee, v38
	v_fmamk_f32 v28, v28, 0x3e0293ee, v38
	v_fmamk_f32 v29, v29, 0x3e0293ee, v38
	v_fmamk_f32 v30, v30, 0x3e0293ee, v38
	v_fmamk_f32 v31, v31, 0x3e0293ee, v38
	v_fmamk_f32 v32, v32, 0x3e0293ee, v38
	v_exp_f32_e32 v127, v18
	v_exp_f32_e32 v129, v19
	v_exp_f32_e32 v125, v20
	v_exp_f32_e32 v128, v21
	v_exp_f32_e32 v123, v22
	v_exp_f32_e32 v126, v23
	v_exp_f32_e32 v122, v24
	v_exp_f32_e32 v124, v25
	v_exp_f32_e32 v119, v26
	v_exp_f32_e32 v121, v27
	v_exp_f32_e32 v117, v28
	v_exp_f32_e32 v120, v29
	v_exp_f32_e32 v115, v30
	v_exp_f32_e32 v118, v31
	v_exp_f32_e32 v114, v32
	v_exp_f32_e32 v116, v39
	s_waitcnt vmcnt(0)
	s_waitcnt lgkmcnt(0)
	s_barrier
	v_mov_b32_e32 v17, 0
	s_cmp_lt_i32 s68, 3
	v_cmp_gt_u32_e64 s[0:1], 32, v165
	s_cbranch_scc1 .LBB0_584
	s_add_i32 s30, 0, 0x4000
	s_cmp_eq_u32 s20, 0
	v_add_u32_e32 v195, s30, v171
	s_cselect_b64 s[30:31], -1, 0
	s_lshl_b32 s38, s63, 6
	s_add_i32 s38, s69, s38
	v_lshlrev_b32_e32 v2, 2, v168
	s_add_i32 s71, s38, s22
	v_mov_b32_e32 v178, 0
	v_sub_u32_e32 v196, s71, v2
	s_sub_i32 s72, 0, s63
	s_lshl_b32 s73, s28, 8
	s_mul_i32 s74, s28, 0x180
	s_mov_b32 s75, 1
	v_mov_b32_e32 v50, 0
	v_mov_b32_e32 v51, v178
	v_mov_b32_e32 v52, v178
	v_mov_b32_e32 v53, v178
	v_mov_b32_e32 v54, v178
	v_mov_b32_e32 v55, v178
	v_mov_b32_e32 v56, v178
	v_mov_b32_e32 v57, v178
	v_mov_b32_e32 v58, v178
	v_mov_b32_e32 v59, v178
	v_mov_b32_e32 v60, v178
	v_mov_b32_e32 v61, v178
	v_mov_b32_e32 v62, v178
	v_mov_b32_e32 v63, v178
	v_mov_b32_e32 v64, v178
	v_mov_b32_e32 v65, v178
	v_mov_b32_e32 v34, 0
	v_mov_b32_e32 v35, v178
	v_mov_b32_e32 v36, v178
	v_mov_b32_e32 v37, v178
	v_mov_b32_e32 v38, v178
	v_mov_b32_e32 v39, v178
	v_mov_b32_e32 v40, v178
	v_mov_b32_e32 v41, v178
	v_mov_b32_e32 v42, v178
	v_mov_b32_e32 v43, v178
	v_mov_b32_e32 v44, v178
	v_mov_b32_e32 v45, v178
	v_mov_b32_e32 v46, v178
	v_mov_b32_e32 v47, v178
	v_mov_b32_e32 v48, v178
	v_mov_b32_e32 v49, v178
	v_mov_b32_e32 v18, 0
	v_mov_b32_e32 v19, v178
	v_mov_b32_e32 v20, v178
	v_mov_b32_e32 v21, v178
	v_mov_b32_e32 v22, v178
	v_mov_b32_e32 v23, v178
	v_mov_b32_e32 v24, v178
	v_mov_b32_e32 v25, v178
	v_mov_b32_e32 v26, v178
	v_mov_b32_e32 v27, v178
	v_mov_b32_e32 v28, v178
	v_mov_b32_e32 v29, v178
	v_mov_b32_e32 v30, v178
	v_mov_b32_e32 v31, v178
	v_mov_b32_e32 v32, v178
	v_mov_b32_e32 v33, v178
	v_mov_b32_e32 v2, 0
	v_mov_b32_e32 v3, v178
	v_mov_b32_e32 v4, v178
	v_mov_b32_e32 v5, v178
	v_mov_b32_e32 v6, v178
	v_mov_b32_e32 v7, v178
	v_mov_b32_e32 v8, v178
	v_mov_b32_e32 v9, v178
	v_mov_b32_e32 v10, v178
	v_mov_b32_e32 v11, v178
	v_mov_b32_e32 v12, v178
	v_mov_b32_e32 v13, v178
	v_mov_b32_e32 v14, v178
	v_mov_b32_e32 v15, v178
	v_mov_b32_e32 v16, v178
	v_mov_b32_e32 v17, v178
